# k30: k28 + FFN-down prologue conv fix-up loop batched (3 load batches instead of 11 dependent round trips, conv-state copy loads issued with them)
# speedup vs baseline: 1.0283x; 1.0018x over previous
; __device__ __forceinline__ unsigned f2bf(float f) { unsigned u = __builtin_bit_cast(unsigned, f); return (u + 0x7fffu + ((u >> 16) & 1u)) >> 16; }
; __device__ __forceinline__ float siluf_(float x) { return x * __builtin_amdgcn_rcpf(1.f + __expf(-x)); }
; __device__ __forceinline__ void ffn_fixup_tile(Frame& F, int layer, int pm, bool conv_out) {
;     ...
;     for (int i = F.tid; i < 2 * DFF; i += NWAVES * 64) {
;         const int wr = i / DFF, ch = i - wr * DFF, grp = 2 * pm + wr;
;         const int r0 = 128 * grp;
;         const int pg = (r0 % 2048 == 0) ? GRP_META : grp - 1;
;         const float um2 = F_SBL(F)[(size_t)(pg * 2 + 0) * DFF + ch], um1 = F_SBL(F)[(size_t)(pg * 2 + 1) * DFF + ch];
;         const float u0 = F_SBF(F)[(size_t)((grp * 2 + 0) * 2 + 0) * DFF + ch], g0 = F_SBF(F)[(size_t)((grp * 2 + 0) * 2 + 1) * DFF + ch];
;         const float u1 = F_SBF(F)[(size_t)((grp * 2 + 1) * 2 + 0) * DFF + ch], g1 = F_SBF(F)[(size_t)((grp * 2 + 1) * 2 + 1) * DFF + ch];
;         const float w0 = cw[ch], w1 = cw[DFF + ch], w2 = cw[2 * DFF + ch], bb = cb[ch];
;         const float c0 = bb + w0 * um2 + w1 * um1 + w2 * u0, c1 = bb + w0 * um1 + w1 * u0 + w2 * u1;
;         H[(size_t)r0 * DFF + ch] = (bf16)f2bf(siluf_(c0) * g0);
;         H[(size_t)(r0 + 1) * DFF + ch] = (bf16)f2bf(siluf_(c1) * g1);
;         if (conv_out && (pm & 7) == 7 && wr == 1) {
;             float* fo = F.out + O_FP + ((size_t)layer * 8 + (pm >> 3)) * 2 * DFF;
;             fo[ch] = F_SBL(F)[(size_t)(grp * 2 + 0) * DFF + ch]; fo[DFF + ch] = F_SBL(F)[(size_t)(grp * 2 + 1) * DFF + ch];
;         }
;     }
.LBB0_337:
	s_mov_b32 s32, 0x2e8ba2e9
	s_movk_i32 s62, 0xf500
	s_add_u32 s58, s6, 0x2c00
	s_addc_u32 s59, s7, 0
	s_add_u32 s60, s6, 0x5800
	s_addc_u32 s61, s7, 0
	s_add_u32 s68, s24, 0x2c00
	s_addc_u32 s69, s25, 0
	v_mov_b32_e32 v6, v2
	v_mul_hi_i32 v0, v6, s32
	v_lshrrev_b32_e32 v1, 31, v0
	v_ashrrev_i32_e32 v0, 9, v0
	v_add_u32_e32 v0, v0, v1
	v_cmp_eq_u32_e64 s[56:57], 1, v0
	v_add_u32_e32 v4, s40, v0
	v_mad_i32_i24 v22, v0, s62, v6
	v_and_b32_e32 v0, 15, v4
	v_lshlrev_b32_e32 v5, 1, v4
	v_add_u32_e32 v1, -2, v5
	v_cmp_ne_u32_e32 vcc, 0, v0
	v_ashrrev_i32_e32 v23, 31, v22
	v_mov_b64_e32 v[12:13], s[46:47]
	v_cndmask_b32_e32 v9, v216, v1, vcc
	s_and_b64 s[56:57], s[56:57], s[22:23]
	s_and_b64 s[56:57], s[56:57], s[20:21]
	v_mad_i64_i32 v[10:11], s[28:29], v9, s80, v[12:13]
	v_lshlrev_b64 v[24:25], 2, v[22:23]
	v_lshl_add_u64 v[10:11], v[10:11], 0, v[24:25]
	global_load_dword v26, v[10:11], off
	v_or_b32_e32 v0, 1, v9
	v_mad_i64_i32 v[10:11], s[28:29], v0, s80, v[12:13]
	v_lshlrev_b32_e32 v94, 7, v4
	v_lshl_add_u64 v[10:11], v[10:11], 0, v[24:25]
	v_lshlrev_b32_e32 v8, 2, v4
	v_mov_b64_e32 v[14:15], s[30:31]
	global_load_dword v27, v[10:11], off
	v_mad_i64_i32 v[10:11], s[28:29], v8, s80, v[14:15]
	v_lshl_add_u64 v[10:11], v[10:11], 0, v[24:25]
	global_load_dword v28, v[10:11], off
	v_or_b32_e32 v0, 1, v8
	v_mad_i64_i32 v[10:11], s[28:29], v0, s80, v[14:15]
	v_lshl_add_u64 v[10:11], v[10:11], 0, v[24:25]
	global_load_dword v29, v[10:11], off
	v_or_b32_e32 v7, 1, v5
	v_lshlrev_b32_e32 v0, 1, v7
	v_mad_i64_i32 v[10:11], s[28:29], v0, s80, v[14:15]
	v_lshl_add_u64 v[10:11], v[10:11], 0, v[24:25]
	global_load_dword v30, v[10:11], off
	v_or_b32_e32 v0, 1, v0
	v_mad_i64_i32 v[10:11], s[28:29], v0, s80, v[14:15]
	v_lshl_add_u64 v[10:11], v[10:11], 0, v[24:25]
	global_load_dword v31, v[10:11], off
	v_lshl_add_u64 v[10:11], s[6:7], 0, v[24:25]
	global_load_dword v32, v[10:11], off
	v_lshl_add_u64 v[16:17], s[58:59], 0, v[24:25]
	global_load_dword v33, v[16:17], off
	v_lshl_add_u64 v[10:11], s[60:61], 0, v[24:25]
	global_load_dword v34, v[10:11], off
	v_lshl_add_u64 v[16:17], s[8:9], 0, v[24:25]
	global_load_dword v35, v[16:17], off
	v_mad_i64_i32 v[10:11], s[28:29], v5, s80, v[12:13]
	v_lshl_add_u64 v[10:11], v[10:11], 0, v[24:25]
	global_load_dword v36, v[10:11], off
	v_mad_i64_i32 v[10:11], s[28:29], v7, s80, v[12:13]
	v_lshl_add_u64 v[10:11], v[10:11], 0, v[24:25]
	global_load_dword v37, v[10:11], off
	v_add_u32_e32 v6, 0x200, v2
	v_mul_hi_i32 v0, v6, s32
	v_lshrrev_b32_e32 v1, 31, v0
	v_ashrrev_i32_e32 v0, 9, v0
	v_add_u32_e32 v0, v0, v1
	v_cmp_eq_u32_e64 s[70:71], 1, v0
	v_add_u32_e32 v4, s40, v0
	v_mad_i32_i24 v96, v0, s62, v6
	v_and_b32_e32 v0, 15, v4
	v_lshlrev_b32_e32 v5, 1, v4
	v_add_u32_e32 v1, -2, v5
	v_cmp_ne_u32_e32 vcc, 0, v0
	v_ashrrev_i32_e32 v97, 31, v96
	v_mov_b64_e32 v[12:13], s[46:47]
	v_cndmask_b32_e32 v9, v216, v1, vcc
	s_and_b64 s[70:71], s[70:71], s[22:23]
	s_and_b64 s[70:71], s[70:71], s[20:21]
	v_mad_i64_i32 v[10:11], s[28:29], v9, s80, v[12:13]
	v_lshlrev_b64 v[98:99], 2, v[96:97]
	v_lshl_add_u64 v[10:11], v[10:11], 0, v[98:99]
	global_load_dword v95, v[10:11], off
	v_or_b32_e32 v0, 1, v9
	v_mad_i64_i32 v[10:11], s[28:29], v0, s80, v[12:13]
	v_lshlrev_b32_e32 v111, 7, v4
	v_lshl_add_u64 v[10:11], v[10:11], 0, v[98:99]
	v_lshlrev_b32_e32 v8, 2, v4
	v_mov_b64_e32 v[14:15], s[30:31]
	global_load_dword v100, v[10:11], off
	v_mad_i64_i32 v[10:11], s[28:29], v8, s80, v[14:15]
	v_lshl_add_u64 v[10:11], v[10:11], 0, v[98:99]
	global_load_dword v101, v[10:11], off
	v_or_b32_e32 v0, 1, v8
	v_mad_i64_i32 v[10:11], s[28:29], v0, s80, v[14:15]
	v_lshl_add_u64 v[10:11], v[10:11], 0, v[98:99]
	global_load_dword v102, v[10:11], off
	v_or_b32_e32 v7, 1, v5
	v_lshlrev_b32_e32 v0, 1, v7
	v_mad_i64_i32 v[10:11], s[28:29], v0, s80, v[14:15]
	v_lshl_add_u64 v[10:11], v[10:11], 0, v[98:99]
	global_load_dword v103, v[10:11], off
	v_or_b32_e32 v0, 1, v0
	v_mad_i64_i32 v[10:11], s[28:29], v0, s80, v[14:15]
	v_lshl_add_u64 v[10:11], v[10:11], 0, v[98:99]
	global_load_dword v104, v[10:11], off
	v_lshl_add_u64 v[10:11], s[6:7], 0, v[98:99]
	global_load_dword v105, v[10:11], off
	v_lshl_add_u64 v[16:17], s[58:59], 0, v[98:99]
	global_load_dword v106, v[16:17], off
	v_lshl_add_u64 v[10:11], s[60:61], 0, v[98:99]
	global_load_dword v107, v[10:11], off
	v_lshl_add_u64 v[16:17], s[8:9], 0, v[98:99]
	global_load_dword v108, v[16:17], off
	v_mad_i64_i32 v[10:11], s[28:29], v5, s80, v[12:13]
	v_lshl_add_u64 v[10:11], v[10:11], 0, v[98:99]
	global_load_dword v109, v[10:11], off
	v_mad_i64_i32 v[10:11], s[28:29], v7, s80, v[12:13]
	v_lshl_add_u64 v[10:11], v[10:11], 0, v[98:99]
	global_load_dword v110, v[10:11], off
	v_add_u32_e32 v6, 0x400, v2
	v_mul_hi_i32 v0, v6, s32
	v_lshrrev_b32_e32 v1, 31, v0
	v_ashrrev_i32_e32 v0, 9, v0
	v_add_u32_e32 v0, v0, v1
	v_cmp_eq_u32_e64 s[98:99], 1, v0
	v_add_u32_e32 v4, s40, v0
	v_mad_i32_i24 v112, v0, s62, v6
	v_and_b32_e32 v0, 15, v4
	v_lshlrev_b32_e32 v5, 1, v4
	v_add_u32_e32 v1, -2, v5
	v_cmp_ne_u32_e32 vcc, 0, v0
	v_ashrrev_i32_e32 v113, 31, v112
	v_mov_b64_e32 v[12:13], s[46:47]
	v_cndmask_b32_e32 v9, v216, v1, vcc
	s_and_b64 s[98:99], s[98:99], s[22:23]
	s_and_b64 s[98:99], s[98:99], s[20:21]
	v_mad_i64_i32 v[10:11], s[28:29], v9, s80, v[12:13]
	v_lshlrev_b64 v[114:115], 2, v[112:113]
	v_lshl_add_u64 v[10:11], v[10:11], 0, v[114:115]
	global_load_dword v116, v[10:11], off
	v_or_b32_e32 v0, 1, v9
	v_mad_i64_i32 v[10:11], s[28:29], v0, s80, v[12:13]
	v_lshlrev_b32_e32 v129, 7, v4
	v_lshl_add_u64 v[10:11], v[10:11], 0, v[114:115]
	v_lshlrev_b32_e32 v8, 2, v4
	v_mov_b64_e32 v[14:15], s[30:31]
	global_load_dword v117, v[10:11], off
; __device__ __forceinline__ unsigned f2bf(float f) { unsigned u = __builtin_bit_cast(unsigned, f); return (u + 0x7fffu + ((u >> 16) & 1u)) >> 16; }
; __device__ __forceinline__ float siluf_(float x) { return x * __builtin_amdgcn_rcpf(1.f + __expf(-x)); }
; __device__ __forceinline__ void ffn_fixup_tile(Frame& F, int layer, int pm, bool conv_out) {
;     ...
;     for (int i = F.tid; i < 2 * DFF; i += NWAVES * 64) {
;         const int wr = i / DFF, ch = i - wr * DFF, grp = 2 * pm + wr;
;         const int r0 = 128 * grp;
;         const int pg = (r0 % 2048 == 0) ? GRP_META : grp - 1;
;         const float um2 = F_SBL(F)[(size_t)(pg * 2 + 0) * DFF + ch], um1 = F_SBL(F)[(size_t)(pg * 2 + 1) * DFF + ch];
;         const float u0 = F_SBF(F)[(size_t)((grp * 2 + 0) * 2 + 0) * DFF + ch], g0 = F_SBF(F)[(size_t)((grp * 2 + 0) * 2 + 1) * DFF + ch];
;         const float u1 = F_SBF(F)[(size_t)((grp * 2 + 1) * 2 + 0) * DFF + ch], g1 = F_SBF(F)[(size_t)((grp * 2 + 1) * 2 + 1) * DFF + ch];
;         const float w0 = cw[ch], w1 = cw[DFF + ch], w2 = cw[2 * DFF + ch], bb = cb[ch];
;         const float c0 = bb + w0 * um2 + w1 * um1 + w2 * u0, c1 = bb + w0 * um1 + w1 * u0 + w2 * u1;
;         H[(size_t)r0 * DFF + ch] = (bf16)f2bf(siluf_(c0) * g0);
;         H[(size_t)(r0 + 1) * DFF + ch] = (bf16)f2bf(siluf_(c1) * g1);
	v_mad_i64_i32 v[10:11], s[28:29], v8, s80, v[14:15]
	v_lshl_add_u64 v[10:11], v[10:11], 0, v[114:115]
	global_load_dword v118, v[10:11], off
	v_or_b32_e32 v0, 1, v8
	v_mad_i64_i32 v[10:11], s[28:29], v0, s80, v[14:15]
	v_lshl_add_u64 v[10:11], v[10:11], 0, v[114:115]
	global_load_dword v119, v[10:11], off
	v_or_b32_e32 v7, 1, v5
	v_lshlrev_b32_e32 v0, 1, v7
	v_mad_i64_i32 v[10:11], s[28:29], v0, s80, v[14:15]
	v_lshl_add_u64 v[10:11], v[10:11], 0, v[114:115]
	global_load_dword v120, v[10:11], off
	v_or_b32_e32 v0, 1, v0
	v_mad_i64_i32 v[10:11], s[28:29], v0, s80, v[14:15]
	v_lshl_add_u64 v[10:11], v[10:11], 0, v[114:115]
	global_load_dword v121, v[10:11], off
	v_lshl_add_u64 v[10:11], s[6:7], 0, v[114:115]
	global_load_dword v122, v[10:11], off
	v_lshl_add_u64 v[16:17], s[58:59], 0, v[114:115]
	global_load_dword v123, v[16:17], off
	v_lshl_add_u64 v[10:11], s[60:61], 0, v[114:115]
	global_load_dword v124, v[10:11], off
	v_lshl_add_u64 v[16:17], s[8:9], 0, v[114:115]
	global_load_dword v125, v[16:17], off
	v_mad_i64_i32 v[10:11], s[28:29], v5, s80, v[12:13]
	v_lshl_add_u64 v[10:11], v[10:11], 0, v[114:115]
	global_load_dword v126, v[10:11], off
	v_mad_i64_i32 v[10:11], s[28:29], v7, s80, v[12:13]
	v_lshl_add_u64 v[10:11], v[10:11], 0, v[114:115]
	global_load_dword v127, v[10:11], off
	v_add_u32_e32 v6, 0x600, v2
	v_mul_hi_i32 v0, v6, s32
	v_lshrrev_b32_e32 v1, 31, v0
	v_ashrrev_i32_e32 v0, 9, v0
	v_add_u32_e32 v0, v0, v1
	v_cmp_eq_u32_e64 s[100:101], 1, v0
	v_add_u32_e32 v4, s40, v0
	v_mad_i32_i24 v130, v0, s62, v6
	v_and_b32_e32 v0, 15, v4
	v_lshlrev_b32_e32 v5, 1, v4
	v_add_u32_e32 v1, -2, v5
	v_cmp_ne_u32_e32 vcc, 0, v0
	v_ashrrev_i32_e32 v131, 31, v130
	v_mov_b64_e32 v[12:13], s[46:47]
	v_cndmask_b32_e32 v9, v216, v1, vcc
	s_and_b64 s[100:101], s[100:101], s[22:23]
	s_and_b64 s[100:101], s[100:101], s[20:21]
	v_mad_i64_i32 v[10:11], s[28:29], v9, s80, v[12:13]
	v_lshlrev_b64 v[132:133], 2, v[130:131]
	v_lshl_add_u64 v[10:11], v[10:11], 0, v[132:133]
	global_load_dword v134, v[10:11], off
	v_or_b32_e32 v0, 1, v9
	v_mad_i64_i32 v[10:11], s[28:29], v0, s80, v[12:13]
	v_lshlrev_b32_e32 v178, 7, v4
	v_lshl_add_u64 v[10:11], v[10:11], 0, v[132:133]
	v_lshlrev_b32_e32 v8, 2, v4
	v_mov_b64_e32 v[14:15], s[30:31]
	global_load_dword v135, v[10:11], off
	v_mad_i64_i32 v[10:11], s[28:29], v8, s80, v[14:15]
	v_lshl_add_u64 v[10:11], v[10:11], 0, v[132:133]
	global_load_dword v136, v[10:11], off
	v_or_b32_e32 v0, 1, v8
	v_mad_i64_i32 v[10:11], s[28:29], v0, s80, v[14:15]
	v_lshl_add_u64 v[10:11], v[10:11], 0, v[132:133]
	global_load_dword v137, v[10:11], off
	v_or_b32_e32 v7, 1, v5
	v_lshlrev_b32_e32 v0, 1, v7
	v_mad_i64_i32 v[10:11], s[28:29], v0, s80, v[14:15]
	v_lshl_add_u64 v[10:11], v[10:11], 0, v[132:133]
	global_load_dword v138, v[10:11], off
	v_or_b32_e32 v0, 1, v0
	v_mad_i64_i32 v[10:11], s[28:29], v0, s80, v[14:15]
	v_lshl_add_u64 v[10:11], v[10:11], 0, v[132:133]
	global_load_dword v139, v[10:11], off
	v_lshl_add_u64 v[10:11], s[6:7], 0, v[132:133]
	global_load_dword v140, v[10:11], off
	v_lshl_add_u64 v[16:17], s[58:59], 0, v[132:133]
	global_load_dword v141, v[16:17], off
	v_lshl_add_u64 v[10:11], s[60:61], 0, v[132:133]
	global_load_dword v142, v[10:11], off
	v_lshl_add_u64 v[16:17], s[8:9], 0, v[132:133]
	global_load_dword v143, v[16:17], off
	v_mad_i64_i32 v[10:11], s[28:29], v5, s80, v[12:13]
	v_lshl_add_u64 v[10:11], v[10:11], 0, v[132:133]
	global_load_dword v176, v[10:11], off
	v_mad_i64_i32 v[10:11], s[28:29], v7, s80, v[12:13]
	v_lshl_add_u64 v[10:11], v[10:11], 0, v[132:133]
	global_load_dword v177, v[10:11], off
	s_waitcnt vmcnt(36)
	v_fma_f32 v0, v26, v32, v35
	v_fmac_f32_e32 v0, v27, v33
	v_fmac_f32_e32 v0, v28, v34
	v_mul_f32_e32 v1, 0xbfb8aa3b, v0
	v_exp_f32_e32 v1, v1
	v_fmac_f32_e32 v35, v27, v32
	v_fmac_f32_e32 v35, v28, v33
	v_fmac_f32_e32 v35, v30, v34
	v_add_f32_e32 v1, 1.0, v1
	v_rcp_f32_e32 v1, v1
	v_mul_f32_e32 v4, 0xbfb8aa3b, v35
	v_exp_f32_e32 v4, v4
	v_mul_f32_e32 v0, v0, v1
	v_mul_f32_e32 v29, v29, v0
	v_add_f32_e32 v4, 1.0, v4
	v_rcp_f32_e32 v4, v4
	v_bfe_u32 v0, v29, 16, 1
	v_add3_u32 v29, v29, v0, s82
	v_mul_f32_e32 v35, v35, v4
	v_mul_f32_e32 v31, v31, v35
	v_bfe_u32 v0, v31, 16, 1
	v_add3_u32 v31, v31, v0, s82
	s_waitcnt vmcnt(24)
	v_fma_f32 v0, v95, v105, v108
	v_fmac_f32_e32 v0, v100, v106
	v_fmac_f32_e32 v0, v101, v107
	v_mul_f32_e32 v1, 0xbfb8aa3b, v0
	v_exp_f32_e32 v1, v1
	v_fmac_f32_e32 v108, v100, v105
	v_fmac_f32_e32 v108, v101, v106
	v_fmac_f32_e32 v108, v103, v107
	v_add_f32_e32 v1, 1.0, v1
	v_rcp_f32_e32 v1, v1
	v_mul_f32_e32 v4, 0xbfb8aa3b, v108
	v_exp_f32_e32 v4, v4
	v_mul_f32_e32 v0, v0, v1
	v_mul_f32_e32 v102, v102, v0
	v_add_f32_e32 v4, 1.0, v4
	v_rcp_f32_e32 v4, v4
	v_bfe_u32 v0, v102, 16, 1
	v_add3_u32 v102, v102, v0, s82
	v_mul_f32_e32 v108, v108, v4
	v_mul_f32_e32 v104, v104, v108
	v_bfe_u32 v0, v104, 16, 1
	v_add3_u32 v104, v104, v0, s82
	s_waitcnt vmcnt(12)
	v_fma_f32 v0, v116, v122, v125
	v_fmac_f32_e32 v0, v117, v123
	v_fmac_f32_e32 v0, v118, v124
	v_mul_f32_e32 v1, 0xbfb8aa3b, v0
	v_exp_f32_e32 v1, v1
	v_fmac_f32_e32 v125, v117, v122
	v_fmac_f32_e32 v125, v118, v123
	v_fmac_f32_e32 v125, v120, v124
	v_add_f32_e32 v1, 1.0, v1
	v_rcp_f32_e32 v1, v1
	v_mul_f32_e32 v4, 0xbfb8aa3b, v125
	v_exp_f32_e32 v4, v4
	v_mul_f32_e32 v0, v0, v1
	v_mul_f32_e32 v119, v119, v0
	v_add_f32_e32 v4, 1.0, v4
	v_rcp_f32_e32 v4, v4
	v_bfe_u32 v0, v119, 16, 1
	v_add3_u32 v119, v119, v0, s82
	v_mul_f32_e32 v125, v125, v4
	v_mul_f32_e32 v121, v121, v125
	v_bfe_u32 v0, v121, 16, 1
	v_add3_u32 v121, v121, v0, s82
	s_waitcnt vmcnt(0)
; __device__ __forceinline__ unsigned f2bf(float f) { unsigned u = __builtin_bit_cast(unsigned, f); return (u + 0x7fffu + ((u >> 16) & 1u)) >> 16; }
; __device__ __forceinline__ float siluf_(float x) { return x * __builtin_amdgcn_rcpf(1.f + __expf(-x)); }
; __device__ __forceinline__ void ffn_fixup_tile(Frame& F, int layer, int pm, bool conv_out) {
;     ...
;     for (int i = F.tid; i < 2 * DFF; i += NWAVES * 64) {
;         const int wr = i / DFF, ch = i - wr * DFF, grp = 2 * pm + wr;
;         const int r0 = 128 * grp;
;         const int pg = (r0 % 2048 == 0) ? GRP_META : grp - 1;
;         const float um2 = F_SBL(F)[(size_t)(pg * 2 + 0) * DFF + ch], um1 = F_SBL(F)[(size_t)(pg * 2 + 1) * DFF + ch];
;         const float u0 = F_SBF(F)[(size_t)((grp * 2 + 0) * 2 + 0) * DFF + ch], g0 = F_SBF(F)[(size_t)((grp * 2 + 0) * 2 + 1) * DFF + ch];
;         const float u1 = F_SBF(F)[(size_t)((grp * 2 + 1) * 2 + 0) * DFF + ch], g1 = F_SBF(F)[(size_t)((grp * 2 + 1) * 2 + 1) * DFF + ch];
;         const float w0 = cw[ch], w1 = cw[DFF + ch], w2 = cw[2 * DFF + ch], bb = cb[ch];
;         const float c0 = bb + w0 * um2 + w1 * um1 + w2 * u0, c1 = bb + w0 * um1 + w1 * u0 + w2 * u1;
;         H[(size_t)r0 * DFF + ch] = (bf16)f2bf(siluf_(c0) * g0);
;         H[(size_t)(r0 + 1) * DFF + ch] = (bf16)f2bf(siluf_(c1) * g1);
;         if (conv_out && (pm & 7) == 7 && wr == 1) {
;             float* fo = F.out + O_FP + ((size_t)layer * 8 + (pm >> 3)) * 2 * DFF;
;             fo[ch] = F_SBL(F)[(size_t)(grp * 2 + 0) * DFF + ch]; fo[DFF + ch] = F_SBL(F)[(size_t)(grp * 2 + 1) * DFF + ch];
;         }
;     }
	v_fma_f32 v0, v134, v140, v143
	v_fmac_f32_e32 v0, v135, v141
	v_fmac_f32_e32 v0, v136, v142
	v_mul_f32_e32 v1, 0xbfb8aa3b, v0
	v_exp_f32_e32 v1, v1
	v_fmac_f32_e32 v143, v135, v140
	v_fmac_f32_e32 v143, v136, v141
	v_fmac_f32_e32 v143, v138, v142
	v_add_f32_e32 v1, 1.0, v1
	v_rcp_f32_e32 v1, v1
	v_mul_f32_e32 v4, 0xbfb8aa3b, v143
	v_exp_f32_e32 v4, v4
	v_mul_f32_e32 v0, v0, v1
	v_mul_f32_e32 v137, v137, v0
	v_add_f32_e32 v4, 1.0, v4
	v_rcp_f32_e32 v4, v4
	v_bfe_u32 v0, v137, 16, 1
	v_add3_u32 v137, v137, v0, s82
	v_mul_f32_e32 v143, v143, v4
	v_mul_f32_e32 v139, v139, v143
	v_bfe_u32 v0, v139, 16, 1
	v_add3_u32 v139, v139, v0, s82
	v_mov_b64_e32 v[12:13], s[64:65]
	v_mad_i64_i32 v[10:11], s[28:29], v94, s38, v[12:13]
	v_lshlrev_b64 v[16:17], 1, v[22:23]
	v_lshl_add_u64 v[10:11], v[10:11], 0, v[16:17]
	global_store_short_d16_hi v[10:11], v29, off
	v_or_b32_e32 v0, 1, v94
	v_mad_i64_i32 v[10:11], s[28:29], v0, s38, v[12:13]
	v_lshl_add_u64 v[10:11], v[10:11], 0, v[16:17]
	global_store_short_d16_hi v[10:11], v31, off
	s_mov_b64 s[26:27], exec
	s_and_b64 exec, exec, s[56:57]
	v_lshl_add_u64 v[10:11], s[24:25], 0, v[24:25]
	global_store_dword v[10:11], v36, off
	v_lshl_add_u64 v[16:17], s[68:69], 0, v[24:25]
	global_store_dword v[16:17], v37, off
	s_mov_b64 exec, s[26:27]
	v_mov_b64_e32 v[12:13], s[64:65]
	v_mad_i64_i32 v[10:11], s[28:29], v111, s38, v[12:13]
	v_lshlrev_b64 v[16:17], 1, v[96:97]
	v_lshl_add_u64 v[10:11], v[10:11], 0, v[16:17]
	global_store_short_d16_hi v[10:11], v102, off
	v_or_b32_e32 v0, 1, v111
	v_mad_i64_i32 v[10:11], s[28:29], v0, s38, v[12:13]
	v_lshl_add_u64 v[10:11], v[10:11], 0, v[16:17]
	global_store_short_d16_hi v[10:11], v104, off
	s_mov_b64 s[26:27], exec
	s_and_b64 exec, exec, s[70:71]
	v_lshl_add_u64 v[10:11], s[24:25], 0, v[98:99]
	global_store_dword v[10:11], v109, off
	v_lshl_add_u64 v[16:17], s[68:69], 0, v[98:99]
	global_store_dword v[16:17], v110, off
	s_mov_b64 exec, s[26:27]
	v_mov_b64_e32 v[12:13], s[64:65]
	v_mad_i64_i32 v[10:11], s[28:29], v129, s38, v[12:13]
	v_lshlrev_b64 v[16:17], 1, v[112:113]
	v_lshl_add_u64 v[10:11], v[10:11], 0, v[16:17]
	global_store_short_d16_hi v[10:11], v119, off
	v_or_b32_e32 v0, 1, v129
	v_mad_i64_i32 v[10:11], s[28:29], v0, s38, v[12:13]
	v_lshl_add_u64 v[10:11], v[10:11], 0, v[16:17]
	global_store_short_d16_hi v[10:11], v121, off
	s_mov_b64 s[26:27], exec
	s_and_b64 exec, exec, s[98:99]
	v_lshl_add_u64 v[10:11], s[24:25], 0, v[114:115]
	global_store_dword v[10:11], v126, off
	v_lshl_add_u64 v[16:17], s[68:69], 0, v[114:115]
	global_store_dword v[16:17], v127, off
	s_mov_b64 exec, s[26:27]
	v_mov_b64_e32 v[12:13], s[64:65]
	v_mad_i64_i32 v[10:11], s[28:29], v178, s38, v[12:13]
	v_lshlrev_b64 v[16:17], 1, v[130:131]
	v_lshl_add_u64 v[10:11], v[10:11], 0, v[16:17]
	global_store_short_d16_hi v[10:11], v137, off
	v_or_b32_e32 v0, 1, v178
	v_mad_i64_i32 v[10:11], s[28:29], v0, s38, v[12:13]
	v_lshl_add_u64 v[10:11], v[10:11], 0, v[16:17]
	global_store_short_d16_hi v[10:11], v139, off
	s_mov_b64 s[26:27], exec
	s_and_b64 exec, exec, s[100:101]
	v_lshl_add_u64 v[10:11], s[24:25], 0, v[132:133]
	global_store_dword v[10:11], v176, off
	v_lshl_add_u64 v[16:17], s[68:69], 0, v[132:133]
	global_store_dword v[16:17], v177, off
	s_mov_b64 exec, s[26:27]
	v_add_u32_e32 v6, 0x800, v2
	v_mul_hi_i32 v0, v6, s32
	v_lshrrev_b32_e32 v1, 31, v0
	v_ashrrev_i32_e32 v0, 9, v0
	v_add_u32_e32 v0, v0, v1
	v_cmp_eq_u32_e64 s[56:57], 1, v0
	v_add_u32_e32 v4, s40, v0
	v_mad_i32_i24 v22, v0, s62, v6
	v_and_b32_e32 v0, 15, v4
	v_lshlrev_b32_e32 v5, 1, v4
	v_add_u32_e32 v1, -2, v5
	v_cmp_ne_u32_e32 vcc, 0, v0
	v_ashrrev_i32_e32 v23, 31, v22
	v_mov_b64_e32 v[12:13], s[46:47]
	v_cndmask_b32_e32 v9, v216, v1, vcc
	s_and_b64 s[56:57], s[56:57], s[22:23]
	s_and_b64 s[56:57], s[56:57], s[20:21]
	v_mad_i64_i32 v[10:11], s[28:29], v9, s80, v[12:13]
	v_lshlrev_b64 v[24:25], 2, v[22:23]
	v_lshl_add_u64 v[10:11], v[10:11], 0, v[24:25]
	global_load_dword v26, v[10:11], off
	v_or_b32_e32 v0, 1, v9
	v_mad_i64_i32 v[10:11], s[28:29], v0, s80, v[12:13]
	v_lshlrev_b32_e32 v94, 7, v4
	v_lshl_add_u64 v[10:11], v[10:11], 0, v[24:25]
	v_lshlrev_b32_e32 v8, 2, v4
	v_mov_b64_e32 v[14:15], s[30:31]
	global_load_dword v27, v[10:11], off
	v_mad_i64_i32 v[10:11], s[28:29], v8, s80, v[14:15]
	v_lshl_add_u64 v[10:11], v[10:11], 0, v[24:25]
	global_load_dword v28, v[10:11], off
	v_or_b32_e32 v0, 1, v8
	v_mad_i64_i32 v[10:11], s[28:29], v0, s80, v[14:15]
	v_lshl_add_u64 v[10:11], v[10:11], 0, v[24:25]
	global_load_dword v29, v[10:11], off
	v_or_b32_e32 v7, 1, v5
	v_lshlrev_b32_e32 v0, 1, v7
	v_mad_i64_i32 v[10:11], s[28:29], v0, s80, v[14:15]
	v_lshl_add_u64 v[10:11], v[10:11], 0, v[24:25]
	global_load_dword v30, v[10:11], off
	v_or_b32_e32 v0, 1, v0
	v_mad_i64_i32 v[10:11], s[28:29], v0, s80, v[14:15]
	v_lshl_add_u64 v[10:11], v[10:11], 0, v[24:25]
	global_load_dword v31, v[10:11], off
	v_lshl_add_u64 v[10:11], s[6:7], 0, v[24:25]
	global_load_dword v32, v[10:11], off
	v_lshl_add_u64 v[16:17], s[58:59], 0, v[24:25]
	global_load_dword v33, v[16:17], off
	v_lshl_add_u64 v[10:11], s[60:61], 0, v[24:25]
	global_load_dword v34, v[10:11], off
	v_lshl_add_u64 v[16:17], s[8:9], 0, v[24:25]
	global_load_dword v35, v[16:17], off
	v_mad_i64_i32 v[10:11], s[28:29], v5, s80, v[12:13]
	v_lshl_add_u64 v[10:11], v[10:11], 0, v[24:25]
	global_load_dword v36, v[10:11], off
	v_mad_i64_i32 v[10:11], s[28:29], v7, s80, v[12:13]
	v_lshl_add_u64 v[10:11], v[10:11], 0, v[24:25]
	global_load_dword v37, v[10:11], off
	v_add_u32_e32 v6, 0xa00, v2
	v_mul_hi_i32 v0, v6, s32
	v_lshrrev_b32_e32 v1, 31, v0
	v_ashrrev_i32_e32 v0, 9, v0
	v_add_u32_e32 v0, v0, v1
; __device__ __forceinline__ void ffn_fixup_tile(Frame& F, int layer, int pm, bool conv_out) {
;     ...
;     for (int i = F.tid; i < 2 * DFF; i += NWAVES * 64) {
;         const int wr = i / DFF, ch = i - wr * DFF, grp = 2 * pm + wr;
;         const int r0 = 128 * grp;
;         const int pg = (r0 % 2048 == 0) ? GRP_META : grp - 1;
;         const float um2 = F_SBL(F)[(size_t)(pg * 2 + 0) * DFF + ch], um1 = F_SBL(F)[(size_t)(pg * 2 + 1) * DFF + ch];
;         const float u0 = F_SBF(F)[(size_t)((grp * 2 + 0) * 2 + 0) * DFF + ch], g0 = F_SBF(F)[(size_t)((grp * 2 + 0) * 2 + 1) * DFF + ch];
;         const float u1 = F_SBF(F)[(size_t)((grp * 2 + 1) * 2 + 0) * DFF + ch], g1 = F_SBF(F)[(size_t)((grp * 2 + 1) * 2 + 1) * DFF + ch];
;         const float w0 = cw[ch], w1 = cw[DFF + ch], w2 = cw[2 * DFF + ch], bb = cb[ch];
;         const float c0 = bb + w0 * um2 + w1 * um1 + w2 * u0, c1 = bb + w0 * um1 + w1 * u0 + w2 * u1;
	v_cmp_eq_u32_e64 s[70:71], 1, v0
	v_add_u32_e32 v4, s40, v0
	v_mad_i32_i24 v96, v0, s62, v6
	v_and_b32_e32 v0, 15, v4
	v_lshlrev_b32_e32 v5, 1, v4
	v_add_u32_e32 v1, -2, v5
	v_cmp_ne_u32_e32 vcc, 0, v0
	v_ashrrev_i32_e32 v97, 31, v96
	v_mov_b64_e32 v[12:13], s[46:47]
	v_cndmask_b32_e32 v9, v216, v1, vcc
	s_and_b64 s[70:71], s[70:71], s[22:23]
	s_and_b64 s[70:71], s[70:71], s[20:21]
	v_mad_i64_i32 v[10:11], s[28:29], v9, s80, v[12:13]
	v_lshlrev_b64 v[98:99], 2, v[96:97]
	v_lshl_add_u64 v[10:11], v[10:11], 0, v[98:99]
	global_load_dword v95, v[10:11], off
	v_or_b32_e32 v0, 1, v9
	v_mad_i64_i32 v[10:11], s[28:29], v0, s80, v[12:13]
	v_lshlrev_b32_e32 v111, 7, v4
	v_lshl_add_u64 v[10:11], v[10:11], 0, v[98:99]
	v_lshlrev_b32_e32 v8, 2, v4
	v_mov_b64_e32 v[14:15], s[30:31]
	global_load_dword v100, v[10:11], off
	v_mad_i64_i32 v[10:11], s[28:29], v8, s80, v[14:15]
	v_lshl_add_u64 v[10:11], v[10:11], 0, v[98:99]
	global_load_dword v101, v[10:11], off
	v_or_b32_e32 v0, 1, v8
	v_mad_i64_i32 v[10:11], s[28:29], v0, s80, v[14:15]
	v_lshl_add_u64 v[10:11], v[10:11], 0, v[98:99]
	global_load_dword v102, v[10:11], off
	v_or_b32_e32 v7, 1, v5
	v_lshlrev_b32_e32 v0, 1, v7
	v_mad_i64_i32 v[10:11], s[28:29], v0, s80, v[14:15]
	v_lshl_add_u64 v[10:11], v[10:11], 0, v[98:99]
	global_load_dword v103, v[10:11], off
	v_or_b32_e32 v0, 1, v0
	v_mad_i64_i32 v[10:11], s[28:29], v0, s80, v[14:15]
	v_lshl_add_u64 v[10:11], v[10:11], 0, v[98:99]
	global_load_dword v104, v[10:11], off
	v_lshl_add_u64 v[10:11], s[6:7], 0, v[98:99]
	global_load_dword v105, v[10:11], off
	v_lshl_add_u64 v[16:17], s[58:59], 0, v[98:99]
	global_load_dword v106, v[16:17], off
	v_lshl_add_u64 v[10:11], s[60:61], 0, v[98:99]
	global_load_dword v107, v[10:11], off
	v_lshl_add_u64 v[16:17], s[8:9], 0, v[98:99]
	global_load_dword v108, v[16:17], off
	v_mad_i64_i32 v[10:11], s[28:29], v5, s80, v[12:13]
	v_lshl_add_u64 v[10:11], v[10:11], 0, v[98:99]
	global_load_dword v109, v[10:11], off
	v_mad_i64_i32 v[10:11], s[28:29], v7, s80, v[12:13]
	v_lshl_add_u64 v[10:11], v[10:11], 0, v[98:99]
	global_load_dword v110, v[10:11], off
	v_add_u32_e32 v6, 0xc00, v2
	v_mul_hi_i32 v0, v6, s32
	v_lshrrev_b32_e32 v1, 31, v0
	v_ashrrev_i32_e32 v0, 9, v0
	v_add_u32_e32 v0, v0, v1
	v_cmp_eq_u32_e64 s[98:99], 1, v0
	v_add_u32_e32 v4, s40, v0
	v_mad_i32_i24 v112, v0, s62, v6
	v_and_b32_e32 v0, 15, v4
	v_lshlrev_b32_e32 v5, 1, v4
	v_add_u32_e32 v1, -2, v5
	v_cmp_ne_u32_e32 vcc, 0, v0
	v_ashrrev_i32_e32 v113, 31, v112
	v_mov_b64_e32 v[12:13], s[46:47]
	v_cndmask_b32_e32 v9, v216, v1, vcc
	s_and_b64 s[98:99], s[98:99], s[22:23]
	s_and_b64 s[98:99], s[98:99], s[20:21]
	v_mad_i64_i32 v[10:11], s[28:29], v9, s80, v[12:13]
	v_lshlrev_b64 v[114:115], 2, v[112:113]
	v_lshl_add_u64 v[10:11], v[10:11], 0, v[114:115]
	global_load_dword v116, v[10:11], off
	v_or_b32_e32 v0, 1, v9
	v_mad_i64_i32 v[10:11], s[28:29], v0, s80, v[12:13]
	v_lshlrev_b32_e32 v129, 7, v4
	v_lshl_add_u64 v[10:11], v[10:11], 0, v[114:115]
	v_lshlrev_b32_e32 v8, 2, v4
	v_mov_b64_e32 v[14:15], s[30:31]
	global_load_dword v117, v[10:11], off
	v_mad_i64_i32 v[10:11], s[28:29], v8, s80, v[14:15]
	v_lshl_add_u64 v[10:11], v[10:11], 0, v[114:115]
	global_load_dword v118, v[10:11], off
	v_or_b32_e32 v0, 1, v8
	v_mad_i64_i32 v[10:11], s[28:29], v0, s80, v[14:15]
	v_lshl_add_u64 v[10:11], v[10:11], 0, v[114:115]
	global_load_dword v119, v[10:11], off
	v_or_b32_e32 v7, 1, v5
	v_lshlrev_b32_e32 v0, 1, v7
	v_mad_i64_i32 v[10:11], s[28:29], v0, s80, v[14:15]
	v_lshl_add_u64 v[10:11], v[10:11], 0, v[114:115]
	global_load_dword v120, v[10:11], off
	v_or_b32_e32 v0, 1, v0
	v_mad_i64_i32 v[10:11], s[28:29], v0, s80, v[14:15]
	v_lshl_add_u64 v[10:11], v[10:11], 0, v[114:115]
	global_load_dword v121, v[10:11], off
	v_lshl_add_u64 v[10:11], s[6:7], 0, v[114:115]
	global_load_dword v122, v[10:11], off
	v_lshl_add_u64 v[16:17], s[58:59], 0, v[114:115]
	global_load_dword v123, v[16:17], off
	v_lshl_add_u64 v[10:11], s[60:61], 0, v[114:115]
	global_load_dword v124, v[10:11], off
	v_lshl_add_u64 v[16:17], s[8:9], 0, v[114:115]
	global_load_dword v125, v[16:17], off
	v_mad_i64_i32 v[10:11], s[28:29], v5, s80, v[12:13]
	v_lshl_add_u64 v[10:11], v[10:11], 0, v[114:115]
	global_load_dword v126, v[10:11], off
	v_mad_i64_i32 v[10:11], s[28:29], v7, s80, v[12:13]
	v_lshl_add_u64 v[10:11], v[10:11], 0, v[114:115]
	global_load_dword v127, v[10:11], off
	v_add_u32_e32 v6, 0xe00, v2
	v_mul_hi_i32 v0, v6, s32
	v_lshrrev_b32_e32 v1, 31, v0
	v_ashrrev_i32_e32 v0, 9, v0
	v_add_u32_e32 v0, v0, v1
	v_cmp_eq_u32_e64 s[100:101], 1, v0
	v_add_u32_e32 v4, s40, v0
	v_mad_i32_i24 v130, v0, s62, v6
	v_and_b32_e32 v0, 15, v4
	v_lshlrev_b32_e32 v5, 1, v4
	v_add_u32_e32 v1, -2, v5
	v_cmp_ne_u32_e32 vcc, 0, v0
	v_ashrrev_i32_e32 v131, 31, v130
	v_mov_b64_e32 v[12:13], s[46:47]
	v_cndmask_b32_e32 v9, v216, v1, vcc
	s_and_b64 s[100:101], s[100:101], s[22:23]
	s_and_b64 s[100:101], s[100:101], s[20:21]
	v_mad_i64_i32 v[10:11], s[28:29], v9, s80, v[12:13]
	v_lshlrev_b64 v[132:133], 2, v[130:131]
	v_lshl_add_u64 v[10:11], v[10:11], 0, v[132:133]
	global_load_dword v134, v[10:11], off
	v_or_b32_e32 v0, 1, v9
	v_mad_i64_i32 v[10:11], s[28:29], v0, s80, v[12:13]
	v_lshlrev_b32_e32 v178, 7, v4
	v_lshl_add_u64 v[10:11], v[10:11], 0, v[132:133]
	v_lshlrev_b32_e32 v8, 2, v4
	v_mov_b64_e32 v[14:15], s[30:31]
	global_load_dword v135, v[10:11], off
	v_mad_i64_i32 v[10:11], s[28:29], v8, s80, v[14:15]
	v_lshl_add_u64 v[10:11], v[10:11], 0, v[132:133]
	global_load_dword v136, v[10:11], off
	v_or_b32_e32 v0, 1, v8
	v_mad_i64_i32 v[10:11], s[28:29], v0, s80, v[14:15]
	v_lshl_add_u64 v[10:11], v[10:11], 0, v[132:133]
	global_load_dword v137, v[10:11], off
	v_or_b32_e32 v7, 1, v5
	v_lshlrev_b32_e32 v0, 1, v7
	v_mad_i64_i32 v[10:11], s[28:29], v0, s80, v[14:15]
	v_lshl_add_u64 v[10:11], v[10:11], 0, v[132:133]
	global_load_dword v138, v[10:11], off
	v_or_b32_e32 v0, 1, v0
	v_mad_i64_i32 v[10:11], s[28:29], v0, s80, v[14:15]
	v_lshl_add_u64 v[10:11], v[10:11], 0, v[132:133]
	global_load_dword v139, v[10:11], off
	v_lshl_add_u64 v[10:11], s[6:7], 0, v[132:133]
	global_load_dword v140, v[10:11], off
	v_lshl_add_u64 v[16:17], s[58:59], 0, v[132:133]
	global_load_dword v141, v[16:17], off
	v_lshl_add_u64 v[10:11], s[60:61], 0, v[132:133]
	global_load_dword v142, v[10:11], off
	v_lshl_add_u64 v[16:17], s[8:9], 0, v[132:133]
	global_load_dword v143, v[16:17], off
	v_mad_i64_i32 v[10:11], s[28:29], v5, s80, v[12:13]
	v_lshl_add_u64 v[10:11], v[10:11], 0, v[132:133]
	global_load_dword v176, v[10:11], off
	v_mad_i64_i32 v[10:11], s[28:29], v7, s80, v[12:13]
	v_lshl_add_u64 v[10:11], v[10:11], 0, v[132:133]
	global_load_dword v177, v[10:11], off
	s_waitcnt vmcnt(36)
; __device__ __forceinline__ unsigned f2bf(float f) { unsigned u = __builtin_bit_cast(unsigned, f); return (u + 0x7fffu + ((u >> 16) & 1u)) >> 16; }
; __device__ __forceinline__ float siluf_(float x) { return x * __builtin_amdgcn_rcpf(1.f + __expf(-x)); }
; __device__ __forceinline__ void ffn_fixup_tile(Frame& F, int layer, int pm, bool conv_out) {
;     ...
;     for (int i = F.tid; i < 2 * DFF; i += NWAVES * 64) {
;         const int wr = i / DFF, ch = i - wr * DFF, grp = 2 * pm + wr;
;         const int r0 = 128 * grp;
;         const int pg = (r0 % 2048 == 0) ? GRP_META : grp - 1;
;         const float um2 = F_SBL(F)[(size_t)(pg * 2 + 0) * DFF + ch], um1 = F_SBL(F)[(size_t)(pg * 2 + 1) * DFF + ch];
;         const float u0 = F_SBF(F)[(size_t)((grp * 2 + 0) * 2 + 0) * DFF + ch], g0 = F_SBF(F)[(size_t)((grp * 2 + 0) * 2 + 1) * DFF + ch];
;         const float u1 = F_SBF(F)[(size_t)((grp * 2 + 1) * 2 + 0) * DFF + ch], g1 = F_SBF(F)[(size_t)((grp * 2 + 1) * 2 + 1) * DFF + ch];
;         const float w0 = cw[ch], w1 = cw[DFF + ch], w2 = cw[2 * DFF + ch], bb = cb[ch];
;         const float c0 = bb + w0 * um2 + w1 * um1 + w2 * u0, c1 = bb + w0 * um1 + w1 * u0 + w2 * u1;
;         H[(size_t)r0 * DFF + ch] = (bf16)f2bf(siluf_(c0) * g0);
;         H[(size_t)(r0 + 1) * DFF + ch] = (bf16)f2bf(siluf_(c1) * g1);
;         if (conv_out && (pm & 7) == 7 && wr == 1) {
;             float* fo = F.out + O_FP + ((size_t)layer * 8 + (pm >> 3)) * 2 * DFF;
;             fo[ch] = F_SBL(F)[(size_t)(grp * 2 + 0) * DFF + ch]; fo[DFF + ch] = F_SBL(F)[(size_t)(grp * 2 + 1) * DFF + ch];
;         }
;     }
	v_fma_f32 v0, v26, v32, v35
	v_fmac_f32_e32 v0, v27, v33
	v_fmac_f32_e32 v0, v28, v34
	v_mul_f32_e32 v1, 0xbfb8aa3b, v0
	v_exp_f32_e32 v1, v1
	v_fmac_f32_e32 v35, v27, v32
	v_fmac_f32_e32 v35, v28, v33
	v_fmac_f32_e32 v35, v30, v34
	v_add_f32_e32 v1, 1.0, v1
	v_rcp_f32_e32 v1, v1
	v_mul_f32_e32 v4, 0xbfb8aa3b, v35
	v_exp_f32_e32 v4, v4
	v_mul_f32_e32 v0, v0, v1
	v_mul_f32_e32 v29, v29, v0
	v_add_f32_e32 v4, 1.0, v4
	v_rcp_f32_e32 v4, v4
	v_bfe_u32 v0, v29, 16, 1
	v_add3_u32 v29, v29, v0, s82
	v_mul_f32_e32 v35, v35, v4
	v_mul_f32_e32 v31, v31, v35
	v_bfe_u32 v0, v31, 16, 1
	v_add3_u32 v31, v31, v0, s82
	s_waitcnt vmcnt(24)
	v_fma_f32 v0, v95, v105, v108
	v_fmac_f32_e32 v0, v100, v106
	v_fmac_f32_e32 v0, v101, v107
	v_mul_f32_e32 v1, 0xbfb8aa3b, v0
	v_exp_f32_e32 v1, v1
	v_fmac_f32_e32 v108, v100, v105
	v_fmac_f32_e32 v108, v101, v106
	v_fmac_f32_e32 v108, v103, v107
	v_add_f32_e32 v1, 1.0, v1
	v_rcp_f32_e32 v1, v1
	v_mul_f32_e32 v4, 0xbfb8aa3b, v108
	v_exp_f32_e32 v4, v4
	v_mul_f32_e32 v0, v0, v1
	v_mul_f32_e32 v102, v102, v0
	v_add_f32_e32 v4, 1.0, v4
	v_rcp_f32_e32 v4, v4
	v_bfe_u32 v0, v102, 16, 1
	v_add3_u32 v102, v102, v0, s82
	v_mul_f32_e32 v108, v108, v4
	v_mul_f32_e32 v104, v104, v108
	v_bfe_u32 v0, v104, 16, 1
	v_add3_u32 v104, v104, v0, s82
	s_waitcnt vmcnt(12)
	v_fma_f32 v0, v116, v122, v125
	v_fmac_f32_e32 v0, v117, v123
	v_fmac_f32_e32 v0, v118, v124
	v_mul_f32_e32 v1, 0xbfb8aa3b, v0
	v_exp_f32_e32 v1, v1
	v_fmac_f32_e32 v125, v117, v122
	v_fmac_f32_e32 v125, v118, v123
	v_fmac_f32_e32 v125, v120, v124
	v_add_f32_e32 v1, 1.0, v1
	v_rcp_f32_e32 v1, v1
	v_mul_f32_e32 v4, 0xbfb8aa3b, v125
	v_exp_f32_e32 v4, v4
	v_mul_f32_e32 v0, v0, v1
	v_mul_f32_e32 v119, v119, v0
	v_add_f32_e32 v4, 1.0, v4
	v_rcp_f32_e32 v4, v4
	v_bfe_u32 v0, v119, 16, 1
	v_add3_u32 v119, v119, v0, s82
	v_mul_f32_e32 v125, v125, v4
	v_mul_f32_e32 v121, v121, v125
	v_bfe_u32 v0, v121, 16, 1
	v_add3_u32 v121, v121, v0, s82
	s_waitcnt vmcnt(0)
	v_fma_f32 v0, v134, v140, v143
	v_fmac_f32_e32 v0, v135, v141
	v_fmac_f32_e32 v0, v136, v142
	v_mul_f32_e32 v1, 0xbfb8aa3b, v0
	v_exp_f32_e32 v1, v1
	v_fmac_f32_e32 v143, v135, v140
	v_fmac_f32_e32 v143, v136, v141
	v_fmac_f32_e32 v143, v138, v142
	v_add_f32_e32 v1, 1.0, v1
	v_rcp_f32_e32 v1, v1
	v_mul_f32_e32 v4, 0xbfb8aa3b, v143
	v_exp_f32_e32 v4, v4
	v_mul_f32_e32 v0, v0, v1
	v_mul_f32_e32 v137, v137, v0
	v_add_f32_e32 v4, 1.0, v4
	v_rcp_f32_e32 v4, v4
	v_bfe_u32 v0, v137, 16, 1
	v_add3_u32 v137, v137, v0, s82
	v_mul_f32_e32 v143, v143, v4
	v_mul_f32_e32 v139, v139, v143
	v_bfe_u32 v0, v139, 16, 1
	v_add3_u32 v139, v139, v0, s82
	v_mov_b64_e32 v[12:13], s[64:65]
	v_mad_i64_i32 v[10:11], s[28:29], v94, s38, v[12:13]
	v_lshlrev_b64 v[16:17], 1, v[22:23]
	v_lshl_add_u64 v[10:11], v[10:11], 0, v[16:17]
	global_store_short_d16_hi v[10:11], v29, off
	v_or_b32_e32 v0, 1, v94
	v_mad_i64_i32 v[10:11], s[28:29], v0, s38, v[12:13]
	v_lshl_add_u64 v[10:11], v[10:11], 0, v[16:17]
	global_store_short_d16_hi v[10:11], v31, off
	s_mov_b64 s[26:27], exec
	s_and_b64 exec, exec, s[56:57]
	v_lshl_add_u64 v[10:11], s[24:25], 0, v[24:25]
	global_store_dword v[10:11], v36, off
	v_lshl_add_u64 v[16:17], s[68:69], 0, v[24:25]
	global_store_dword v[16:17], v37, off
	s_mov_b64 exec, s[26:27]
	v_mov_b64_e32 v[12:13], s[64:65]
	v_mad_i64_i32 v[10:11], s[28:29], v111, s38, v[12:13]
	v_lshlrev_b64 v[16:17], 1, v[96:97]
	v_lshl_add_u64 v[10:11], v[10:11], 0, v[16:17]
	global_store_short_d16_hi v[10:11], v102, off
	v_or_b32_e32 v0, 1, v111
	v_mad_i64_i32 v[10:11], s[28:29], v0, s38, v[12:13]
	v_lshl_add_u64 v[10:11], v[10:11], 0, v[16:17]
	global_store_short_d16_hi v[10:11], v104, off
	s_mov_b64 s[26:27], exec
	s_and_b64 exec, exec, s[70:71]
	v_lshl_add_u64 v[10:11], s[24:25], 0, v[98:99]
	global_store_dword v[10:11], v109, off
	v_lshl_add_u64 v[16:17], s[68:69], 0, v[98:99]
	global_store_dword v[16:17], v110, off
	s_mov_b64 exec, s[26:27]
	v_mov_b64_e32 v[12:13], s[64:65]
	v_mad_i64_i32 v[10:11], s[28:29], v129, s38, v[12:13]
	v_lshlrev_b64 v[16:17], 1, v[112:113]
	v_lshl_add_u64 v[10:11], v[10:11], 0, v[16:17]
	global_store_short_d16_hi v[10:11], v119, off
	v_or_b32_e32 v0, 1, v129
	v_mad_i64_i32 v[10:11], s[28:29], v0, s38, v[12:13]
	v_lshl_add_u64 v[10:11], v[10:11], 0, v[16:17]
	global_store_short_d16_hi v[10:11], v121, off
	s_mov_b64 s[26:27], exec
	s_and_b64 exec, exec, s[98:99]
	v_lshl_add_u64 v[10:11], s[24:25], 0, v[114:115]
	global_store_dword v[10:11], v126, off
	v_lshl_add_u64 v[16:17], s[68:69], 0, v[114:115]
	global_store_dword v[16:17], v127, off
	s_mov_b64 exec, s[26:27]
	v_mov_b64_e32 v[12:13], s[64:65]
	v_mad_i64_i32 v[10:11], s[28:29], v178, s38, v[12:13]
	v_lshlrev_b64 v[16:17], 1, v[130:131]
	v_lshl_add_u64 v[10:11], v[10:11], 0, v[16:17]
	global_store_short_d16_hi v[10:11], v137, off
	v_or_b32_e32 v0, 1, v178
	v_mad_i64_i32 v[10:11], s[28:29], v0, s38, v[12:13]
	v_lshl_add_u64 v[10:11], v[10:11], 0, v[16:17]
	global_store_short_d16_hi v[10:11], v139, off
	s_mov_b64 s[26:27], exec
	s_and_b64 exec, exec, s[100:101]
	v_lshl_add_u64 v[10:11], s[24:25], 0, v[132:133]
	global_store_dword v[10:11], v176, off
	v_lshl_add_u64 v[16:17], s[68:69], 0, v[132:133]
	global_store_dword v[16:17], v177, off
	s_mov_b64 exec, s[26:27]
	v_add_u32_e32 v6, 0x1000, v2
	v_mul_hi_i32 v0, v6, s32
	v_lshrrev_b32_e32 v1, 31, v0
	v_ashrrev_i32_e32 v0, 9, v0
	v_add_u32_e32 v0, v0, v1
	v_cmp_eq_u32_e64 s[56:57], 1, v0
	v_add_u32_e32 v4, s40, v0
	v_mad_i32_i24 v22, v0, s62, v6
	v_and_b32_e32 v0, 15, v4
	v_lshlrev_b32_e32 v5, 1, v4
	v_add_u32_e32 v1, -2, v5
	v_cmp_ne_u32_e32 vcc, 0, v0
	v_ashrrev_i32_e32 v23, 31, v22
	v_mov_b64_e32 v[12:13], s[46:47]
; __device__ __forceinline__ void ffn_fixup_tile(Frame& F, int layer, int pm, bool conv_out) {
;     ...
;     for (int i = F.tid; i < 2 * DFF; i += NWAVES * 64) {
;         const int wr = i / DFF, ch = i - wr * DFF, grp = 2 * pm + wr;
;         const int r0 = 128 * grp;
;         const int pg = (r0 % 2048 == 0) ? GRP_META : grp - 1;
;         const float um2 = F_SBL(F)[(size_t)(pg * 2 + 0) * DFF + ch], um1 = F_SBL(F)[(size_t)(pg * 2 + 1) * DFF + ch];
;         const float u0 = F_SBF(F)[(size_t)((grp * 2 + 0) * 2 + 0) * DFF + ch], g0 = F_SBF(F)[(size_t)((grp * 2 + 0) * 2 + 1) * DFF + ch];
;         const float u1 = F_SBF(F)[(size_t)((grp * 2 + 1) * 2 + 0) * DFF + ch], g1 = F_SBF(F)[(size_t)((grp * 2 + 1) * 2 + 1) * DFF + ch];
;         const float w0 = cw[ch], w1 = cw[DFF + ch], w2 = cw[2 * DFF + ch], bb = cb[ch];
;         const float c0 = bb + w0 * um2 + w1 * um1 + w2 * u0, c1 = bb + w0 * um1 + w1 * u0 + w2 * u1;
	v_cndmask_b32_e32 v9, v216, v1, vcc
	s_and_b64 s[56:57], s[56:57], s[22:23]
	s_and_b64 s[56:57], s[56:57], s[20:21]
	v_mad_i64_i32 v[10:11], s[28:29], v9, s80, v[12:13]
	v_lshlrev_b64 v[24:25], 2, v[22:23]
	v_lshl_add_u64 v[10:11], v[10:11], 0, v[24:25]
	global_load_dword v26, v[10:11], off
	v_or_b32_e32 v0, 1, v9
	v_mad_i64_i32 v[10:11], s[28:29], v0, s80, v[12:13]
	v_lshlrev_b32_e32 v94, 7, v4
	v_lshl_add_u64 v[10:11], v[10:11], 0, v[24:25]
	v_lshlrev_b32_e32 v8, 2, v4
	v_mov_b64_e32 v[14:15], s[30:31]
	global_load_dword v27, v[10:11], off
	v_mad_i64_i32 v[10:11], s[28:29], v8, s80, v[14:15]
	v_lshl_add_u64 v[10:11], v[10:11], 0, v[24:25]
	global_load_dword v28, v[10:11], off
	v_or_b32_e32 v0, 1, v8
	v_mad_i64_i32 v[10:11], s[28:29], v0, s80, v[14:15]
	v_lshl_add_u64 v[10:11], v[10:11], 0, v[24:25]
	global_load_dword v29, v[10:11], off
	v_or_b32_e32 v7, 1, v5
	v_lshlrev_b32_e32 v0, 1, v7
	v_mad_i64_i32 v[10:11], s[28:29], v0, s80, v[14:15]
	v_lshl_add_u64 v[10:11], v[10:11], 0, v[24:25]
	global_load_dword v30, v[10:11], off
	v_or_b32_e32 v0, 1, v0
	v_mad_i64_i32 v[10:11], s[28:29], v0, s80, v[14:15]
	v_lshl_add_u64 v[10:11], v[10:11], 0, v[24:25]
	global_load_dword v31, v[10:11], off
	v_lshl_add_u64 v[10:11], s[6:7], 0, v[24:25]
	global_load_dword v32, v[10:11], off
	v_lshl_add_u64 v[16:17], s[58:59], 0, v[24:25]
	global_load_dword v33, v[16:17], off
	v_lshl_add_u64 v[10:11], s[60:61], 0, v[24:25]
	global_load_dword v34, v[10:11], off
	v_lshl_add_u64 v[16:17], s[8:9], 0, v[24:25]
	global_load_dword v35, v[16:17], off
	v_mad_i64_i32 v[10:11], s[28:29], v5, s80, v[12:13]
	v_lshl_add_u64 v[10:11], v[10:11], 0, v[24:25]
	global_load_dword v36, v[10:11], off
	v_mad_i64_i32 v[10:11], s[28:29], v7, s80, v[12:13]
	v_lshl_add_u64 v[10:11], v[10:11], 0, v[24:25]
	global_load_dword v37, v[10:11], off
	v_add_u32_e32 v6, 0x1200, v2
	v_mul_hi_i32 v0, v6, s32
	v_lshrrev_b32_e32 v1, 31, v0
	v_ashrrev_i32_e32 v0, 9, v0
	v_add_u32_e32 v0, v0, v1
	v_cmp_eq_u32_e64 s[70:71], 1, v0
	v_add_u32_e32 v4, s40, v0
	v_mad_i32_i24 v96, v0, s62, v6
	v_and_b32_e32 v0, 15, v4
	v_lshlrev_b32_e32 v5, 1, v4
	v_add_u32_e32 v1, -2, v5
	v_cmp_ne_u32_e32 vcc, 0, v0
	v_ashrrev_i32_e32 v97, 31, v96
	v_mov_b64_e32 v[12:13], s[46:47]
	v_cndmask_b32_e32 v9, v216, v1, vcc
	s_and_b64 s[70:71], s[70:71], s[22:23]
	s_and_b64 s[70:71], s[70:71], s[20:21]
	v_mad_i64_i32 v[10:11], s[28:29], v9, s80, v[12:13]
	v_lshlrev_b64 v[98:99], 2, v[96:97]
	v_lshl_add_u64 v[10:11], v[10:11], 0, v[98:99]
	global_load_dword v95, v[10:11], off
	v_or_b32_e32 v0, 1, v9
	v_mad_i64_i32 v[10:11], s[28:29], v0, s80, v[12:13]
	v_lshlrev_b32_e32 v111, 7, v4
	v_lshl_add_u64 v[10:11], v[10:11], 0, v[98:99]
	v_lshlrev_b32_e32 v8, 2, v4
	v_mov_b64_e32 v[14:15], s[30:31]
	global_load_dword v100, v[10:11], off
	v_mad_i64_i32 v[10:11], s[28:29], v8, s80, v[14:15]
	v_lshl_add_u64 v[10:11], v[10:11], 0, v[98:99]
	global_load_dword v101, v[10:11], off
	v_or_b32_e32 v0, 1, v8
	v_mad_i64_i32 v[10:11], s[28:29], v0, s80, v[14:15]
	v_lshl_add_u64 v[10:11], v[10:11], 0, v[98:99]
	global_load_dword v102, v[10:11], off
	v_or_b32_e32 v7, 1, v5
	v_lshlrev_b32_e32 v0, 1, v7
	v_mad_i64_i32 v[10:11], s[28:29], v0, s80, v[14:15]
	v_lshl_add_u64 v[10:11], v[10:11], 0, v[98:99]
	global_load_dword v103, v[10:11], off
	v_or_b32_e32 v0, 1, v0
	v_mad_i64_i32 v[10:11], s[28:29], v0, s80, v[14:15]
	v_lshl_add_u64 v[10:11], v[10:11], 0, v[98:99]
	global_load_dword v104, v[10:11], off
	v_lshl_add_u64 v[10:11], s[6:7], 0, v[98:99]
	global_load_dword v105, v[10:11], off
	v_lshl_add_u64 v[16:17], s[58:59], 0, v[98:99]
	global_load_dword v106, v[16:17], off
	v_lshl_add_u64 v[10:11], s[60:61], 0, v[98:99]
	global_load_dword v107, v[10:11], off
	v_lshl_add_u64 v[16:17], s[8:9], 0, v[98:99]
	global_load_dword v108, v[16:17], off
	v_mad_i64_i32 v[10:11], s[28:29], v5, s80, v[12:13]
	v_lshl_add_u64 v[10:11], v[10:11], 0, v[98:99]
	global_load_dword v109, v[10:11], off
	v_mad_i64_i32 v[10:11], s[28:29], v7, s80, v[12:13]
	v_lshl_add_u64 v[10:11], v[10:11], 0, v[98:99]
	global_load_dword v110, v[10:11], off
	v_add_u32_e32 v6, 0x1400, v2
	v_mul_hi_i32 v0, v6, s32
	v_lshrrev_b32_e32 v1, 31, v0
	v_ashrrev_i32_e32 v0, 9, v0
	v_add_u32_e32 v0, v0, v1
	v_cmp_eq_u32_e64 s[98:99], 1, v0
	v_add_u32_e32 v4, s40, v0
	v_mad_i32_i24 v112, v0, s62, v6
	v_and_b32_e32 v0, 15, v4
	v_lshlrev_b32_e32 v5, 1, v4
	v_add_u32_e32 v1, -2, v5
	v_cmp_ne_u32_e32 vcc, 0, v0
	v_ashrrev_i32_e32 v113, 31, v112
	v_mov_b64_e32 v[12:13], s[46:47]
	v_cndmask_b32_e32 v9, v216, v1, vcc
	s_and_b64 s[98:99], s[98:99], s[22:23]
	s_and_b64 s[98:99], s[98:99], s[20:21]
	v_mad_i64_i32 v[10:11], s[28:29], v9, s80, v[12:13]
	v_lshlrev_b64 v[114:115], 2, v[112:113]
	v_lshl_add_u64 v[10:11], v[10:11], 0, v[114:115]
	global_load_dword v116, v[10:11], off
	v_or_b32_e32 v0, 1, v9
	v_mad_i64_i32 v[10:11], s[28:29], v0, s80, v[12:13]
	v_lshlrev_b32_e32 v129, 7, v4
	v_lshl_add_u64 v[10:11], v[10:11], 0, v[114:115]
	v_lshlrev_b32_e32 v8, 2, v4
	v_mov_b64_e32 v[14:15], s[30:31]
	global_load_dword v117, v[10:11], off
	v_mad_i64_i32 v[10:11], s[28:29], v8, s80, v[14:15]
	v_lshl_add_u64 v[10:11], v[10:11], 0, v[114:115]
	global_load_dword v118, v[10:11], off
	v_or_b32_e32 v0, 1, v8
	v_mad_i64_i32 v[10:11], s[28:29], v0, s80, v[14:15]
	v_lshl_add_u64 v[10:11], v[10:11], 0, v[114:115]
	global_load_dword v119, v[10:11], off
	v_or_b32_e32 v7, 1, v5
	v_lshlrev_b32_e32 v0, 1, v7
	v_mad_i64_i32 v[10:11], s[28:29], v0, s80, v[14:15]
	v_lshl_add_u64 v[10:11], v[10:11], 0, v[114:115]
	global_load_dword v120, v[10:11], off
	v_or_b32_e32 v0, 1, v0
	v_mad_i64_i32 v[10:11], s[28:29], v0, s80, v[14:15]
	v_lshl_add_u64 v[10:11], v[10:11], 0, v[114:115]
	global_load_dword v121, v[10:11], off
	v_lshl_add_u64 v[10:11], s[6:7], 0, v[114:115]
	global_load_dword v122, v[10:11], off
	v_lshl_add_u64 v[16:17], s[58:59], 0, v[114:115]
	global_load_dword v123, v[16:17], off
	v_lshl_add_u64 v[10:11], s[60:61], 0, v[114:115]
	global_load_dword v124, v[10:11], off
	v_lshl_add_u64 v[16:17], s[8:9], 0, v[114:115]
	global_load_dword v125, v[16:17], off
	v_mad_i64_i32 v[10:11], s[28:29], v5, s80, v[12:13]
	v_lshl_add_u64 v[10:11], v[10:11], 0, v[114:115]
	global_load_dword v126, v[10:11], off
	v_mad_i64_i32 v[10:11], s[28:29], v7, s80, v[12:13]
	v_lshl_add_u64 v[10:11], v[10:11], 0, v[114:115]
	global_load_dword v127, v[10:11], off
	s_waitcnt vmcnt(24)
; __device__ __forceinline__ unsigned f2bf(float f) { unsigned u = __builtin_bit_cast(unsigned, f); return (u + 0x7fffu + ((u >> 16) & 1u)) >> 16; }
; __device__ __forceinline__ float siluf_(float x) { return x * __builtin_amdgcn_rcpf(1.f + __expf(-x)); }
; #define REFRESH() do { int t_ = threadIdx.x; asm volatile("" : "+v"(t_)); F.tid = t_; F.lane = t_ & 63; F.wave = __builtin_amdgcn_readfirstlane(t_ >> 6); F.gw = blockIdx.x * NWAVES + F.wave; } while (0)
; __device__ __forceinline__ void ffn_fixup_tile(Frame& F, int layer, int pm, bool conv_out) {
;     ...
;     for (int i = F.tid; i < 2 * DFF; i += NWAVES * 64) {
;         const int wr = i / DFF, ch = i - wr * DFF, grp = 2 * pm + wr;
;         const int r0 = 128 * grp;
;         const int pg = (r0 % 2048 == 0) ? GRP_META : grp - 1;
;         const float um2 = F_SBL(F)[(size_t)(pg * 2 + 0) * DFF + ch], um1 = F_SBL(F)[(size_t)(pg * 2 + 1) * DFF + ch];
;         const float u0 = F_SBF(F)[(size_t)((grp * 2 + 0) * 2 + 0) * DFF + ch], g0 = F_SBF(F)[(size_t)((grp * 2 + 0) * 2 + 1) * DFF + ch];
;         const float u1 = F_SBF(F)[(size_t)((grp * 2 + 1) * 2 + 0) * DFF + ch], g1 = F_SBF(F)[(size_t)((grp * 2 + 1) * 2 + 1) * DFF + ch];
;         const float w0 = cw[ch], w1 = cw[DFF + ch], w2 = cw[2 * DFF + ch], bb = cb[ch];
;         const float c0 = bb + w0 * um2 + w1 * um1 + w2 * u0, c1 = bb + w0 * um1 + w1 * u0 + w2 * u1;
;         H[(size_t)r0 * DFF + ch] = (bf16)f2bf(siluf_(c0) * g0);
;         H[(size_t)(r0 + 1) * DFF + ch] = (bf16)f2bf(siluf_(c1) * g1);
;         if (conv_out && (pm & 7) == 7 && wr == 1) {
;             float* fo = F.out + O_FP + ((size_t)layer * 8 + (pm >> 3)) * 2 * DFF;
;             fo[ch] = F_SBL(F)[(size_t)(grp * 2 + 0) * DFF + ch]; fo[DFF + ch] = F_SBL(F)[(size_t)(grp * 2 + 1) * DFF + ch];
;         }
;     }
; __global__ void __launch_bounds__(NWAVES * 64, 2) fwd_kernel(Args args) {
;     ...
;                 { REFRESH(); pg8::StaticOrder S2; S2.init(st.nt, 1024, Gs, cs, st.tile0); pg8::Unit fu; for (int i = 0; S2.next(i, fu); ++i) ffn_fixup_tile(F, layer, fu.pm, fu.pn == 0); }
	v_fma_f32 v0, v26, v32, v35
	v_fmac_f32_e32 v0, v27, v33
	v_fmac_f32_e32 v0, v28, v34
	v_mul_f32_e32 v1, 0xbfb8aa3b, v0
	v_exp_f32_e32 v1, v1
	v_fmac_f32_e32 v35, v27, v32
	v_fmac_f32_e32 v35, v28, v33
	v_fmac_f32_e32 v35, v30, v34
	v_add_f32_e32 v1, 1.0, v1
	v_rcp_f32_e32 v1, v1
	v_mul_f32_e32 v4, 0xbfb8aa3b, v35
	v_exp_f32_e32 v4, v4
	v_mul_f32_e32 v0, v0, v1
	v_mul_f32_e32 v29, v29, v0
	v_add_f32_e32 v4, 1.0, v4
	v_rcp_f32_e32 v4, v4
	v_bfe_u32 v0, v29, 16, 1
	v_add3_u32 v29, v29, v0, s82
	v_mul_f32_e32 v35, v35, v4
	v_mul_f32_e32 v31, v31, v35
	v_bfe_u32 v0, v31, 16, 1
	v_add3_u32 v31, v31, v0, s82
	s_waitcnt vmcnt(12)
	v_fma_f32 v0, v95, v105, v108
	v_fmac_f32_e32 v0, v100, v106
	v_fmac_f32_e32 v0, v101, v107
	v_mul_f32_e32 v1, 0xbfb8aa3b, v0
	v_exp_f32_e32 v1, v1
	v_fmac_f32_e32 v108, v100, v105
	v_fmac_f32_e32 v108, v101, v106
	v_fmac_f32_e32 v108, v103, v107
	v_add_f32_e32 v1, 1.0, v1
	v_rcp_f32_e32 v1, v1
	v_mul_f32_e32 v4, 0xbfb8aa3b, v108
	v_exp_f32_e32 v4, v4
	v_mul_f32_e32 v0, v0, v1
	v_mul_f32_e32 v102, v102, v0
	v_add_f32_e32 v4, 1.0, v4
	v_rcp_f32_e32 v4, v4
	v_bfe_u32 v0, v102, 16, 1
	v_add3_u32 v102, v102, v0, s82
	v_mul_f32_e32 v108, v108, v4
	v_mul_f32_e32 v104, v104, v108
	v_bfe_u32 v0, v104, 16, 1
	v_add3_u32 v104, v104, v0, s82
	s_waitcnt vmcnt(0)
	v_fma_f32 v0, v116, v122, v125
	v_fmac_f32_e32 v0, v117, v123
	v_fmac_f32_e32 v0, v118, v124
	v_mul_f32_e32 v1, 0xbfb8aa3b, v0
	v_exp_f32_e32 v1, v1
	v_fmac_f32_e32 v125, v117, v122
	v_fmac_f32_e32 v125, v118, v123
	v_fmac_f32_e32 v125, v120, v124
	v_add_f32_e32 v1, 1.0, v1
	v_rcp_f32_e32 v1, v1
	v_mul_f32_e32 v4, 0xbfb8aa3b, v125
	v_exp_f32_e32 v4, v4
	v_mul_f32_e32 v0, v0, v1
	v_mul_f32_e32 v119, v119, v0
	v_add_f32_e32 v4, 1.0, v4
	v_rcp_f32_e32 v4, v4
	v_bfe_u32 v0, v119, 16, 1
	v_add3_u32 v119, v119, v0, s82
	v_mul_f32_e32 v125, v125, v4
	v_mul_f32_e32 v121, v121, v125
	v_bfe_u32 v0, v121, 16, 1
	v_add3_u32 v121, v121, v0, s82
	v_mov_b64_e32 v[12:13], s[64:65]
	v_mad_i64_i32 v[10:11], s[28:29], v94, s38, v[12:13]
	v_lshlrev_b64 v[16:17], 1, v[22:23]
	v_lshl_add_u64 v[10:11], v[10:11], 0, v[16:17]
	global_store_short_d16_hi v[10:11], v29, off
	v_or_b32_e32 v0, 1, v94
	v_mad_i64_i32 v[10:11], s[28:29], v0, s38, v[12:13]
	v_lshl_add_u64 v[10:11], v[10:11], 0, v[16:17]
	global_store_short_d16_hi v[10:11], v31, off
	s_mov_b64 s[26:27], exec
	s_and_b64 exec, exec, s[56:57]
	v_lshl_add_u64 v[10:11], s[24:25], 0, v[24:25]
	global_store_dword v[10:11], v36, off
	v_lshl_add_u64 v[16:17], s[68:69], 0, v[24:25]
	global_store_dword v[16:17], v37, off
	s_mov_b64 exec, s[26:27]
	v_mov_b64_e32 v[12:13], s[64:65]
	v_mad_i64_i32 v[10:11], s[28:29], v111, s38, v[12:13]
	v_lshlrev_b64 v[16:17], 1, v[96:97]
	v_lshl_add_u64 v[10:11], v[10:11], 0, v[16:17]
	global_store_short_d16_hi v[10:11], v102, off
	v_or_b32_e32 v0, 1, v111
	v_mad_i64_i32 v[10:11], s[28:29], v0, s38, v[12:13]
	v_lshl_add_u64 v[10:11], v[10:11], 0, v[16:17]
	global_store_short_d16_hi v[10:11], v104, off
	s_mov_b64 s[26:27], exec
	s_and_b64 exec, exec, s[70:71]
	v_lshl_add_u64 v[10:11], s[24:25], 0, v[98:99]
	global_store_dword v[10:11], v109, off
	v_lshl_add_u64 v[16:17], s[68:69], 0, v[98:99]
	global_store_dword v[16:17], v110, off
	s_mov_b64 exec, s[26:27]
	v_mov_b64_e32 v[12:13], s[64:65]
	v_mad_i64_i32 v[10:11], s[28:29], v129, s38, v[12:13]
	v_lshlrev_b64 v[16:17], 1, v[112:113]
	v_lshl_add_u64 v[10:11], v[10:11], 0, v[16:17]
	global_store_short_d16_hi v[10:11], v119, off
	v_or_b32_e32 v0, 1, v129
	v_mad_i64_i32 v[10:11], s[28:29], v0, s38, v[12:13]
	v_lshl_add_u64 v[10:11], v[10:11], 0, v[16:17]
	global_store_short_d16_hi v[10:11], v121, off
	s_mov_b64 s[26:27], exec
	s_and_b64 exec, exec, s[98:99]
	v_lshl_add_u64 v[10:11], s[24:25], 0, v[114:115]
	global_store_dword v[10:11], v126, off
	v_lshl_add_u64 v[16:17], s[68:69], 0, v[114:115]
	global_store_dword v[16:17], v127, off
	s_mov_b64 exec, s[26:27]
	s_branch .LBB0_325
